# hand-written bias_task (site: ret phase): single load round trip, permlane32/16 swap + DPP reduction instead of 240 ds_bpermute
# speedup vs baseline: 1.0099x; 1.0099x over previous
.LBB0_286:
	v_readlane_b32 s2, v255, 34
	s_nop 3
.Lbias_loop2:
	s_cmpk_gt_i32 s2, 0xaf
	s_cbranch_scc1 .LBB0_291
	v_readlane_b32 s3, v255, 36
	s_nop 3
	s_or_b32 s3, s3, 0x20100
	s_branch .Lbias_task
.Lbias_ret2:
	s_add_i32 s2, s2, s70
	s_branch .Lbias_loop2

.Lbias_task:
	v_writelane_b32 v255, s40, 42
	v_writelane_b32 v255, s41, 43
	v_writelane_b32 v255, s42, 44
	v_writelane_b32 v255, s43, 45
	v_writelane_b32 v255, s44, 46
	v_writelane_b32 v255, s45, 47
	v_writelane_b32 v255, s46, 48
	v_writelane_b32 v255, s47, 49
	v_writelane_b32 v255, s48, 50
	v_writelane_b32 v255, s49, 51
	v_writelane_b32 v255, s50, 52
	v_writelane_b32 v255, s51, 53
	v_writelane_b32 v255, s52, 54
	v_writelane_b32 v255, s53, 55
	s_mov_b64 s[50:51], exec
	v_mul_u32_u24_e32 v0, 0xc0, v228
	ds_write_b128 v0, v[128:131] offset:0
	ds_write_b128 v0, v[132:135] offset:16
	ds_write_b128 v0, v[136:139] offset:32
	ds_write_b128 v0, v[140:143] offset:48
	ds_write_b128 v0, v[144:147] offset:64
	ds_write_b128 v0, v[148:151] offset:80
	ds_write_b128 v0, v[152:155] offset:96
	ds_write_b128 v0, v[156:159] offset:112
	ds_write_b128 v0, v[160:163] offset:128
	ds_write_b128 v0, v[164:167] offset:144
	ds_write_b128 v0, v[168:171] offset:160
	ds_write_b128 v0, v[172:175] offset:176
	s_and_b32 s47, s3, 0xff
	s_bfe_u32 s48, s3, 0x80008
	s_lshr_b32 s49, s3, 16
	v_readlane_b32 s40, v255, 7
	v_readlane_b32 s41, v255, 8
	s_mul_i32 s52, s47, 0x1e000
	s_mul_i32 s53, s48, 0x3000
	s_add_u32 s52, s52, s53
	s_nop 1
	s_add_u32 s40, s40, s52
	s_addc_u32 s41, s41, 0
	s_cmp_eq_u32 s48, 0
	s_cbranch_scc1 .Lbias_w0
	v_readlane_b32 s42, v254, 63
	v_readlane_b32 s43, v255, 0
	s_mul_i32 s52, s47, 0xb00000
	s_mov_b32 s44, s10
	s_mov_b32 s45, s11
	s_mul_i32 s53, s47, 0x1b800
	s_movk_i32 s46, 0x5800
	s_branch .Lbias_w1
.Lbias_w0:
	v_readlane_b32 s42, v254, 59
	v_readlane_b32 s43, v254, 60
	s_mul_i32 s52, s47, 0x580000
	s_mov_b32 s44, s8
	s_mov_b32 s45, s9
	s_mul_i32 s53, s47, 0xdc00
	s_movk_i32 s46, 0x2c00
.Lbias_w1:
	s_nop 1
	s_add_u32 s42, s42, s52
	s_addc_u32 s43, s43, 0
	s_add_u32 s44, s44, s53
	s_addc_u32 s45, s45, 0
	v_and_b32_e32 v160, 63, v229
	v_lshrrev_b32_e32 v161, 6, v229
	v_lshlrev_b32_e32 v162, 6, v160
	v_add_u32_e32 v163, 0x6000, v162
	v_add_u32_e32 v164, 0xc000, v162
	v_add_u32_e32 v165, 0x12000, v162
	v_add_u32_e32 v166, 0x18000, v162
	v_lshlrev_b32_e32 v167, 5, v160
	v_lshl_add_u32 v167, v161, 14, v167
	s_lshl_b32 s52, s2, 16
	v_add_u32_e32 v167, s52, v167
	v_add_u32_e32 v168, 0x1000, v167
	v_add_u32_e32 v169, 0x2000, v167
	v_add_u32_e32 v170, 0x3000, v167
	s_nop 4
	global_load_dwordx4 v[0:3], v162, s[40:41]
	global_load_dwordx4 v[4:7], v162, s[40:41] offset:16
	global_load_dwordx4 v[8:11], v162, s[40:41] offset:32
	global_load_dwordx4 v[12:15], v162, s[40:41] offset:48
	global_load_dwordx4 v[16:19], v163, s[40:41]
	global_load_dwordx4 v[20:23], v163, s[40:41] offset:16
	global_load_dwordx4 v[24:27], v163, s[40:41] offset:32
	global_load_dwordx4 v[28:31], v163, s[40:41] offset:48
	global_load_dwordx4 v[32:35], v164, s[40:41]
	global_load_dwordx4 v[36:39], v164, s[40:41] offset:16
	global_load_dwordx4 v[40:43], v164, s[40:41] offset:32
	global_load_dwordx4 v[44:47], v164, s[40:41] offset:48
	global_load_dwordx4 v[48:51], v165, s[40:41]
	global_load_dwordx4 v[52:55], v165, s[40:41] offset:16
	global_load_dwordx4 v[56:59], v165, s[40:41] offset:32
	global_load_dwordx4 v[60:63], v165, s[40:41] offset:48
	global_load_dwordx4 v[64:67], v166, s[40:41]
	global_load_dwordx4 v[68:71], v166, s[40:41] offset:16
	global_load_dwordx4 v[72:75], v166, s[40:41] offset:32
	global_load_dwordx4 v[76:79], v166, s[40:41] offset:48
	global_load_dwordx4 v[80:83], v167, s[42:43]
	global_load_dwordx4 v[84:87], v167, s[42:43] offset:16
	global_load_dwordx4 v[112:115], v169, s[42:43]
	global_load_dwordx4 v[116:119], v169, s[42:43] offset:16
	global_load_dwordx4 v[88:91], v167, s[42:43] offset:2048
	global_load_dwordx4 v[92:95], v167, s[42:43] offset:2064
	global_load_dwordx4 v[120:123], v169, s[42:43] offset:2048
	global_load_dwordx4 v[124:127], v169, s[42:43] offset:2064
	global_load_dwordx4 v[96:99], v168, s[42:43]
	global_load_dwordx4 v[100:103], v168, s[42:43] offset:16
	global_load_dwordx4 v[128:131], v170, s[42:43]
	global_load_dwordx4 v[132:135], v170, s[42:43] offset:16
	global_load_dwordx4 v[104:107], v168, s[42:43] offset:2048
	global_load_dwordx4 v[108:111], v168, s[42:43] offset:2064
	global_load_dwordx4 v[136:139], v170, s[42:43] offset:2048
	global_load_dwordx4 v[140:143], v170, s[42:43] offset:2064
	s_waitcnt vmcnt(12)
	v_lshlrev_b32_e32 v144, 16, v80
	v_and_b32_e32 v145, 0xffff0000, v80
	v_lshlrev_b32_e32 v146, 16, v81
	v_and_b32_e32 v147, 0xffff0000, v81
	v_lshlrev_b32_e32 v148, 16, v82
	v_and_b32_e32 v149, 0xffff0000, v82
	v_lshlrev_b32_e32 v150, 16, v83
	v_and_b32_e32 v151, 0xffff0000, v83
	v_lshlrev_b32_e32 v152, 16, v84
	v_and_b32_e32 v153, 0xffff0000, v84
	v_lshlrev_b32_e32 v154, 16, v85
	v_and_b32_e32 v155, 0xffff0000, v85
	v_lshlrev_b32_e32 v156, 16, v86
	v_and_b32_e32 v157, 0xffff0000, v86
	v_lshlrev_b32_e32 v158, 16, v87
	v_and_b32_e32 v159, 0xffff0000, v87
	v_pk_mul_f32 v[160:161], v[0:1], v[144:145]
	v_pk_mul_f32 v[162:163], v[8:9], v[152:153]
	v_pk_fma_f32 v[160:161], v[2:3], v[146:147], v[160:161]
	v_pk_fma_f32 v[162:163], v[10:11], v[154:155], v[162:163]
	v_pk_fma_f32 v[160:161], v[4:5], v[148:149], v[160:161]
	v_pk_fma_f32 v[162:163], v[12:13], v[156:157], v[162:163]
	v_pk_fma_f32 v[160:161], v[6:7], v[150:151], v[160:161]
	v_pk_fma_f32 v[162:163], v[14:15], v[158:159], v[162:163]
	v_pk_add_f32 v[160:161], v[160:161], v[162:163]
	s_nop 0
	v_add_f32_e32 v164, v160, v161
	v_pk_mul_f32 v[160:161], v[16:17], v[144:145]
	v_pk_mul_f32 v[162:163], v[24:25], v[152:153]
	v_pk_fma_f32 v[160:161], v[18:19], v[146:147], v[160:161]
	v_pk_fma_f32 v[162:163], v[26:27], v[154:155], v[162:163]
	v_pk_fma_f32 v[160:161], v[20:21], v[148:149], v[160:161]
	v_pk_fma_f32 v[162:163], v[28:29], v[156:157], v[162:163]
	v_pk_fma_f32 v[160:161], v[22:23], v[150:151], v[160:161]
	v_pk_fma_f32 v[162:163], v[30:31], v[158:159], v[162:163]
	v_pk_add_f32 v[160:161], v[160:161], v[162:163]
	s_nop 0
	v_add_f32_e32 v165, v160, v161
	v_pk_mul_f32 v[160:161], v[32:33], v[144:145]
	v_pk_mul_f32 v[162:163], v[40:41], v[152:153]
	v_pk_fma_f32 v[160:161], v[34:35], v[146:147], v[160:161]
	v_pk_fma_f32 v[162:163], v[42:43], v[154:155], v[162:163]
	v_pk_fma_f32 v[160:161], v[36:37], v[148:149], v[160:161]
	v_pk_fma_f32 v[162:163], v[44:45], v[156:157], v[162:163]
	v_pk_fma_f32 v[160:161], v[38:39], v[150:151], v[160:161]
	v_pk_fma_f32 v[162:163], v[46:47], v[158:159], v[162:163]
	v_pk_add_f32 v[160:161], v[160:161], v[162:163]
	s_nop 0
	v_add_f32_e32 v166, v160, v161
	v_pk_mul_f32 v[160:161], v[48:49], v[144:145]
	v_pk_mul_f32 v[162:163], v[56:57], v[152:153]
	v_pk_fma_f32 v[160:161], v[50:51], v[146:147], v[160:161]
	v_pk_fma_f32 v[162:163], v[58:59], v[154:155], v[162:163]
	v_pk_fma_f32 v[160:161], v[52:53], v[148:149], v[160:161]
	v_pk_fma_f32 v[162:163], v[60:61], v[156:157], v[162:163]
	v_pk_fma_f32 v[160:161], v[54:55], v[150:151], v[160:161]
	v_pk_fma_f32 v[162:163], v[62:63], v[158:159], v[162:163]
	v_pk_add_f32 v[160:161], v[160:161], v[162:163]
	s_nop 0
	v_add_f32_e32 v167, v160, v161
	v_pk_mul_f32 v[160:161], v[64:65], v[144:145]
	v_pk_mul_f32 v[162:163], v[72:73], v[152:153]
	v_pk_fma_f32 v[160:161], v[66:67], v[146:147], v[160:161]
	v_pk_fma_f32 v[162:163], v[74:75], v[154:155], v[162:163]
	v_pk_fma_f32 v[160:161], v[68:69], v[148:149], v[160:161]
	v_pk_fma_f32 v[162:163], v[76:77], v[156:157], v[162:163]
	v_pk_fma_f32 v[160:161], v[70:71], v[150:151], v[160:161]
	v_pk_fma_f32 v[162:163], v[78:79], v[158:159], v[162:163]
	v_pk_add_f32 v[160:161], v[160:161], v[162:163]
	s_nop 0
	v_add_f32_e32 v168, v160, v161
	v_lshlrev_b32_e32 v144, 16, v112
	v_and_b32_e32 v145, 0xffff0000, v112
	v_lshlrev_b32_e32 v146, 16, v113
	v_and_b32_e32 v147, 0xffff0000, v113
	v_lshlrev_b32_e32 v148, 16, v114
	v_and_b32_e32 v149, 0xffff0000, v114
	v_lshlrev_b32_e32 v150, 16, v115
	v_and_b32_e32 v151, 0xffff0000, v115
	v_lshlrev_b32_e32 v152, 16, v116
	v_and_b32_e32 v153, 0xffff0000, v116
	v_lshlrev_b32_e32 v154, 16, v117
	v_and_b32_e32 v155, 0xffff0000, v117
	v_lshlrev_b32_e32 v156, 16, v118
	v_and_b32_e32 v157, 0xffff0000, v118
	v_lshlrev_b32_e32 v158, 16, v119
	v_and_b32_e32 v159, 0xffff0000, v119
	v_pk_mul_f32 v[160:161], v[0:1], v[144:145]
	v_pk_mul_f32 v[162:163], v[8:9], v[152:153]
	v_pk_fma_f32 v[160:161], v[2:3], v[146:147], v[160:161]
	v_pk_fma_f32 v[162:163], v[10:11], v[154:155], v[162:163]
	v_pk_fma_f32 v[160:161], v[4:5], v[148:149], v[160:161]
	v_pk_fma_f32 v[162:163], v[12:13], v[156:157], v[162:163]
	v_pk_fma_f32 v[160:161], v[6:7], v[150:151], v[160:161]
	v_pk_fma_f32 v[162:163], v[14:15], v[158:159], v[162:163]
	v_pk_add_f32 v[160:161], v[160:161], v[162:163]
	s_nop 0
	v_add_f32_e32 v169, v160, v161
	v_pk_mul_f32 v[160:161], v[16:17], v[144:145]
	v_pk_mul_f32 v[162:163], v[24:25], v[152:153]
	v_pk_fma_f32 v[160:161], v[18:19], v[146:147], v[160:161]
	v_pk_fma_f32 v[162:163], v[26:27], v[154:155], v[162:163]
	v_pk_fma_f32 v[160:161], v[20:21], v[148:149], v[160:161]
	v_pk_fma_f32 v[162:163], v[28:29], v[156:157], v[162:163]
	v_pk_fma_f32 v[160:161], v[22:23], v[150:151], v[160:161]
	v_pk_fma_f32 v[162:163], v[30:31], v[158:159], v[162:163]
	v_pk_add_f32 v[160:161], v[160:161], v[162:163]
	s_nop 0
	v_add_f32_e32 v170, v160, v161
	v_pk_mul_f32 v[160:161], v[32:33], v[144:145]
	v_pk_mul_f32 v[162:163], v[40:41], v[152:153]
	v_pk_fma_f32 v[160:161], v[34:35], v[146:147], v[160:161]
	v_pk_fma_f32 v[162:163], v[42:43], v[154:155], v[162:163]
	v_pk_fma_f32 v[160:161], v[36:37], v[148:149], v[160:161]
	v_pk_fma_f32 v[162:163], v[44:45], v[156:157], v[162:163]
	v_pk_fma_f32 v[160:161], v[38:39], v[150:151], v[160:161]
	v_pk_fma_f32 v[162:163], v[46:47], v[158:159], v[162:163]
	v_pk_add_f32 v[160:161], v[160:161], v[162:163]
	s_nop 0
	v_add_f32_e32 v171, v160, v161
	v_pk_mul_f32 v[160:161], v[48:49], v[144:145]
	v_pk_mul_f32 v[162:163], v[56:57], v[152:153]
	v_pk_fma_f32 v[160:161], v[50:51], v[146:147], v[160:161]
	v_pk_fma_f32 v[162:163], v[58:59], v[154:155], v[162:163]
	v_pk_fma_f32 v[160:161], v[52:53], v[148:149], v[160:161]
	v_pk_fma_f32 v[162:163], v[60:61], v[156:157], v[162:163]
	v_pk_fma_f32 v[160:161], v[54:55], v[150:151], v[160:161]
	v_pk_fma_f32 v[162:163], v[62:63], v[158:159], v[162:163]
	v_pk_add_f32 v[160:161], v[160:161], v[162:163]
	s_nop 0
	v_add_f32_e32 v172, v160, v161
	v_pk_mul_f32 v[160:161], v[64:65], v[144:145]
	v_pk_mul_f32 v[162:163], v[72:73], v[152:153]
	v_pk_fma_f32 v[160:161], v[66:67], v[146:147], v[160:161]
	v_pk_fma_f32 v[162:163], v[74:75], v[154:155], v[162:163]
	v_pk_fma_f32 v[160:161], v[68:69], v[148:149], v[160:161]
	v_pk_fma_f32 v[162:163], v[76:77], v[156:157], v[162:163]
	v_pk_fma_f32 v[160:161], v[70:71], v[150:151], v[160:161]
	v_pk_fma_f32 v[162:163], v[78:79], v[158:159], v[162:163]
	v_pk_add_f32 v[160:161], v[160:161], v[162:163]
	s_nop 0
	v_add_f32_e32 v173, v160, v161
	s_nop 1
	v_permlane32_swap_b32_e32 v164, v169
	v_permlane32_swap_b32_e32 v165, v170
	v_permlane32_swap_b32_e32 v166, v171
	v_permlane32_swap_b32_e32 v167, v172
	v_permlane32_swap_b32_e32 v168, v173
	s_nop 1
	v_add_f32_e32 v80, v164, v169
	v_add_f32_e32 v81, v165, v170
	v_add_f32_e32 v82, v166, v171
	v_add_f32_e32 v83, v167, v172
	v_add_f32_e32 v84, v168, v173
	s_waitcnt vmcnt(8)
	v_lshlrev_b32_e32 v144, 16, v88
	v_and_b32_e32 v145, 0xffff0000, v88
	v_lshlrev_b32_e32 v146, 16, v89
	v_and_b32_e32 v147, 0xffff0000, v89
	v_lshlrev_b32_e32 v148, 16, v90
	v_and_b32_e32 v149, 0xffff0000, v90
	v_lshlrev_b32_e32 v150, 16, v91
	v_and_b32_e32 v151, 0xffff0000, v91
	v_lshlrev_b32_e32 v152, 16, v92
	v_and_b32_e32 v153, 0xffff0000, v92
	v_lshlrev_b32_e32 v154, 16, v93
	v_and_b32_e32 v155, 0xffff0000, v93
	v_lshlrev_b32_e32 v156, 16, v94
	v_and_b32_e32 v157, 0xffff0000, v94
	v_lshlrev_b32_e32 v158, 16, v95
	v_and_b32_e32 v159, 0xffff0000, v95
	v_pk_mul_f32 v[160:161], v[0:1], v[144:145]
	v_pk_mul_f32 v[162:163], v[8:9], v[152:153]
	v_pk_fma_f32 v[160:161], v[2:3], v[146:147], v[160:161]
	v_pk_fma_f32 v[162:163], v[10:11], v[154:155], v[162:163]
	v_pk_fma_f32 v[160:161], v[4:5], v[148:149], v[160:161]
	v_pk_fma_f32 v[162:163], v[12:13], v[156:157], v[162:163]
	v_pk_fma_f32 v[160:161], v[6:7], v[150:151], v[160:161]
	v_pk_fma_f32 v[162:163], v[14:15], v[158:159], v[162:163]
	v_pk_add_f32 v[160:161], v[160:161], v[162:163]
	s_nop 0
	v_add_f32_e32 v164, v160, v161
	v_pk_mul_f32 v[160:161], v[16:17], v[144:145]
	v_pk_mul_f32 v[162:163], v[24:25], v[152:153]
	v_pk_fma_f32 v[160:161], v[18:19], v[146:147], v[160:161]
	v_pk_fma_f32 v[162:163], v[26:27], v[154:155], v[162:163]
	v_pk_fma_f32 v[160:161], v[20:21], v[148:149], v[160:161]
	v_pk_fma_f32 v[162:163], v[28:29], v[156:157], v[162:163]
	v_pk_fma_f32 v[160:161], v[22:23], v[150:151], v[160:161]
	v_pk_fma_f32 v[162:163], v[30:31], v[158:159], v[162:163]
	v_pk_add_f32 v[160:161], v[160:161], v[162:163]
	s_nop 0
	v_add_f32_e32 v165, v160, v161
	v_pk_mul_f32 v[160:161], v[32:33], v[144:145]
	v_pk_mul_f32 v[162:163], v[40:41], v[152:153]
	v_pk_fma_f32 v[160:161], v[34:35], v[146:147], v[160:161]
	v_pk_fma_f32 v[162:163], v[42:43], v[154:155], v[162:163]
	v_pk_fma_f32 v[160:161], v[36:37], v[148:149], v[160:161]
	v_pk_fma_f32 v[162:163], v[44:45], v[156:157], v[162:163]
	v_pk_fma_f32 v[160:161], v[38:39], v[150:151], v[160:161]
	v_pk_fma_f32 v[162:163], v[46:47], v[158:159], v[162:163]
	v_pk_add_f32 v[160:161], v[160:161], v[162:163]
	s_nop 0
	v_add_f32_e32 v166, v160, v161
	v_pk_mul_f32 v[160:161], v[48:49], v[144:145]
	v_pk_mul_f32 v[162:163], v[56:57], v[152:153]
	v_pk_fma_f32 v[160:161], v[50:51], v[146:147], v[160:161]
	v_pk_fma_f32 v[162:163], v[58:59], v[154:155], v[162:163]
	v_pk_fma_f32 v[160:161], v[52:53], v[148:149], v[160:161]
	v_pk_fma_f32 v[162:163], v[60:61], v[156:157], v[162:163]
	v_pk_fma_f32 v[160:161], v[54:55], v[150:151], v[160:161]
	v_pk_fma_f32 v[162:163], v[62:63], v[158:159], v[162:163]
	v_pk_add_f32 v[160:161], v[160:161], v[162:163]
	s_nop 0
	v_add_f32_e32 v167, v160, v161
	v_pk_mul_f32 v[160:161], v[64:65], v[144:145]
	v_pk_mul_f32 v[162:163], v[72:73], v[152:153]
	v_pk_fma_f32 v[160:161], v[66:67], v[146:147], v[160:161]
	v_pk_fma_f32 v[162:163], v[74:75], v[154:155], v[162:163]
	v_pk_fma_f32 v[160:161], v[68:69], v[148:149], v[160:161]
	v_pk_fma_f32 v[162:163], v[76:77], v[156:157], v[162:163]
	v_pk_fma_f32 v[160:161], v[70:71], v[150:151], v[160:161]
	v_pk_fma_f32 v[162:163], v[78:79], v[158:159], v[162:163]
	v_pk_add_f32 v[160:161], v[160:161], v[162:163]
	s_nop 0
	v_add_f32_e32 v168, v160, v161
	v_lshlrev_b32_e32 v144, 16, v120
	v_and_b32_e32 v145, 0xffff0000, v120
	v_lshlrev_b32_e32 v146, 16, v121
	v_and_b32_e32 v147, 0xffff0000, v121
	v_lshlrev_b32_e32 v148, 16, v122
	v_and_b32_e32 v149, 0xffff0000, v122
	v_lshlrev_b32_e32 v150, 16, v123
	v_and_b32_e32 v151, 0xffff0000, v123
	v_lshlrev_b32_e32 v152, 16, v124
	v_and_b32_e32 v153, 0xffff0000, v124
	v_lshlrev_b32_e32 v154, 16, v125
	v_and_b32_e32 v155, 0xffff0000, v125
	v_lshlrev_b32_e32 v156, 16, v126
	v_and_b32_e32 v157, 0xffff0000, v126
	v_lshlrev_b32_e32 v158, 16, v127
	v_and_b32_e32 v159, 0xffff0000, v127
	v_pk_mul_f32 v[160:161], v[0:1], v[144:145]
	v_pk_mul_f32 v[162:163], v[8:9], v[152:153]
	v_pk_fma_f32 v[160:161], v[2:3], v[146:147], v[160:161]
	v_pk_fma_f32 v[162:163], v[10:11], v[154:155], v[162:163]
	v_pk_fma_f32 v[160:161], v[4:5], v[148:149], v[160:161]
	v_pk_fma_f32 v[162:163], v[12:13], v[156:157], v[162:163]
	v_pk_fma_f32 v[160:161], v[6:7], v[150:151], v[160:161]
	v_pk_fma_f32 v[162:163], v[14:15], v[158:159], v[162:163]
	v_pk_add_f32 v[160:161], v[160:161], v[162:163]
	s_nop 0
	v_add_f32_e32 v169, v160, v161
	v_pk_mul_f32 v[160:161], v[16:17], v[144:145]
	v_pk_mul_f32 v[162:163], v[24:25], v[152:153]
	v_pk_fma_f32 v[160:161], v[18:19], v[146:147], v[160:161]
	v_pk_fma_f32 v[162:163], v[26:27], v[154:155], v[162:163]
	v_pk_fma_f32 v[160:161], v[20:21], v[148:149], v[160:161]
	v_pk_fma_f32 v[162:163], v[28:29], v[156:157], v[162:163]
	v_pk_fma_f32 v[160:161], v[22:23], v[150:151], v[160:161]
	v_pk_fma_f32 v[162:163], v[30:31], v[158:159], v[162:163]
	v_pk_add_f32 v[160:161], v[160:161], v[162:163]
	s_nop 0
	v_add_f32_e32 v170, v160, v161
	v_pk_mul_f32 v[160:161], v[32:33], v[144:145]
	v_pk_mul_f32 v[162:163], v[40:41], v[152:153]
	v_pk_fma_f32 v[160:161], v[34:35], v[146:147], v[160:161]
	v_pk_fma_f32 v[162:163], v[42:43], v[154:155], v[162:163]
	v_pk_fma_f32 v[160:161], v[36:37], v[148:149], v[160:161]
	v_pk_fma_f32 v[162:163], v[44:45], v[156:157], v[162:163]
	v_pk_fma_f32 v[160:161], v[38:39], v[150:151], v[160:161]
	v_pk_fma_f32 v[162:163], v[46:47], v[158:159], v[162:163]
	v_pk_add_f32 v[160:161], v[160:161], v[162:163]
	s_nop 0
	v_add_f32_e32 v171, v160, v161
	v_pk_mul_f32 v[160:161], v[48:49], v[144:145]
	v_pk_mul_f32 v[162:163], v[56:57], v[152:153]
	v_pk_fma_f32 v[160:161], v[50:51], v[146:147], v[160:161]
	v_pk_fma_f32 v[162:163], v[58:59], v[154:155], v[162:163]
	v_pk_fma_f32 v[160:161], v[52:53], v[148:149], v[160:161]
	v_pk_fma_f32 v[162:163], v[60:61], v[156:157], v[162:163]
	v_pk_fma_f32 v[160:161], v[54:55], v[150:151], v[160:161]
	v_pk_fma_f32 v[162:163], v[62:63], v[158:159], v[162:163]
	v_pk_add_f32 v[160:161], v[160:161], v[162:163]
	s_nop 0
	v_add_f32_e32 v172, v160, v161
	v_pk_mul_f32 v[160:161], v[64:65], v[144:145]
	v_pk_mul_f32 v[162:163], v[72:73], v[152:153]
	v_pk_fma_f32 v[160:161], v[66:67], v[146:147], v[160:161]
	v_pk_fma_f32 v[162:163], v[74:75], v[154:155], v[162:163]
	v_pk_fma_f32 v[160:161], v[68:69], v[148:149], v[160:161]
	v_pk_fma_f32 v[162:163], v[76:77], v[156:157], v[162:163]
	v_pk_fma_f32 v[160:161], v[70:71], v[150:151], v[160:161]
	v_pk_fma_f32 v[162:163], v[78:79], v[158:159], v[162:163]
	v_pk_add_f32 v[160:161], v[160:161], v[162:163]
	s_nop 0
	v_add_f32_e32 v173, v160, v161
	s_nop 1
	v_permlane32_swap_b32_e32 v164, v169
	v_permlane32_swap_b32_e32 v165, v170
	v_permlane32_swap_b32_e32 v166, v171
	v_permlane32_swap_b32_e32 v167, v172
	v_permlane32_swap_b32_e32 v168, v173
	s_nop 1
	v_add_f32_e32 v88, v164, v169
	v_add_f32_e32 v89, v165, v170
	v_add_f32_e32 v90, v166, v171
	v_add_f32_e32 v91, v167, v172
	v_add_f32_e32 v92, v168, v173
	s_waitcnt vmcnt(4)
	v_lshlrev_b32_e32 v144, 16, v96
	v_and_b32_e32 v145, 0xffff0000, v96
	v_lshlrev_b32_e32 v146, 16, v97
	v_and_b32_e32 v147, 0xffff0000, v97
	v_lshlrev_b32_e32 v148, 16, v98
	v_and_b32_e32 v149, 0xffff0000, v98
	v_lshlrev_b32_e32 v150, 16, v99
	v_and_b32_e32 v151, 0xffff0000, v99
	v_lshlrev_b32_e32 v152, 16, v100
	v_and_b32_e32 v153, 0xffff0000, v100
	v_lshlrev_b32_e32 v154, 16, v101
	v_and_b32_e32 v155, 0xffff0000, v101
	v_lshlrev_b32_e32 v156, 16, v102
	v_and_b32_e32 v157, 0xffff0000, v102
	v_lshlrev_b32_e32 v158, 16, v103
	v_and_b32_e32 v159, 0xffff0000, v103
	v_pk_mul_f32 v[160:161], v[0:1], v[144:145]
	v_pk_mul_f32 v[162:163], v[8:9], v[152:153]
	v_pk_fma_f32 v[160:161], v[2:3], v[146:147], v[160:161]
	v_pk_fma_f32 v[162:163], v[10:11], v[154:155], v[162:163]
	v_pk_fma_f32 v[160:161], v[4:5], v[148:149], v[160:161]
	v_pk_fma_f32 v[162:163], v[12:13], v[156:157], v[162:163]
	v_pk_fma_f32 v[160:161], v[6:7], v[150:151], v[160:161]
	v_pk_fma_f32 v[162:163], v[14:15], v[158:159], v[162:163]
	v_pk_add_f32 v[160:161], v[160:161], v[162:163]
	s_nop 0
	v_add_f32_e32 v164, v160, v161
	v_pk_mul_f32 v[160:161], v[16:17], v[144:145]
	v_pk_mul_f32 v[162:163], v[24:25], v[152:153]
	v_pk_fma_f32 v[160:161], v[18:19], v[146:147], v[160:161]
	v_pk_fma_f32 v[162:163], v[26:27], v[154:155], v[162:163]
	v_pk_fma_f32 v[160:161], v[20:21], v[148:149], v[160:161]
	v_pk_fma_f32 v[162:163], v[28:29], v[156:157], v[162:163]
	v_pk_fma_f32 v[160:161], v[22:23], v[150:151], v[160:161]
	v_pk_fma_f32 v[162:163], v[30:31], v[158:159], v[162:163]
	v_pk_add_f32 v[160:161], v[160:161], v[162:163]
	s_nop 0
	v_add_f32_e32 v165, v160, v161
	v_pk_mul_f32 v[160:161], v[32:33], v[144:145]
	v_pk_mul_f32 v[162:163], v[40:41], v[152:153]
	v_pk_fma_f32 v[160:161], v[34:35], v[146:147], v[160:161]
	v_pk_fma_f32 v[162:163], v[42:43], v[154:155], v[162:163]
	v_pk_fma_f32 v[160:161], v[36:37], v[148:149], v[160:161]
	v_pk_fma_f32 v[162:163], v[44:45], v[156:157], v[162:163]
	v_pk_fma_f32 v[160:161], v[38:39], v[150:151], v[160:161]
	v_pk_fma_f32 v[162:163], v[46:47], v[158:159], v[162:163]
	v_pk_add_f32 v[160:161], v[160:161], v[162:163]
	s_nop 0
	v_add_f32_e32 v166, v160, v161
	v_pk_mul_f32 v[160:161], v[48:49], v[144:145]
	v_pk_mul_f32 v[162:163], v[56:57], v[152:153]
	v_pk_fma_f32 v[160:161], v[50:51], v[146:147], v[160:161]
	v_pk_fma_f32 v[162:163], v[58:59], v[154:155], v[162:163]
	v_pk_fma_f32 v[160:161], v[52:53], v[148:149], v[160:161]
	v_pk_fma_f32 v[162:163], v[60:61], v[156:157], v[162:163]
	v_pk_fma_f32 v[160:161], v[54:55], v[150:151], v[160:161]
	v_pk_fma_f32 v[162:163], v[62:63], v[158:159], v[162:163]
	v_pk_add_f32 v[160:161], v[160:161], v[162:163]
	s_nop 0
	v_add_f32_e32 v167, v160, v161
	v_pk_mul_f32 v[160:161], v[64:65], v[144:145]
	v_pk_mul_f32 v[162:163], v[72:73], v[152:153]
	v_pk_fma_f32 v[160:161], v[66:67], v[146:147], v[160:161]
	v_pk_fma_f32 v[162:163], v[74:75], v[154:155], v[162:163]
	v_pk_fma_f32 v[160:161], v[68:69], v[148:149], v[160:161]
	v_pk_fma_f32 v[162:163], v[76:77], v[156:157], v[162:163]
	v_pk_fma_f32 v[160:161], v[70:71], v[150:151], v[160:161]
	v_pk_fma_f32 v[162:163], v[78:79], v[158:159], v[162:163]
	v_pk_add_f32 v[160:161], v[160:161], v[162:163]
	s_nop 0
	v_add_f32_e32 v168, v160, v161
	v_lshlrev_b32_e32 v144, 16, v128
	v_and_b32_e32 v145, 0xffff0000, v128
	v_lshlrev_b32_e32 v146, 16, v129
	v_and_b32_e32 v147, 0xffff0000, v129
	v_lshlrev_b32_e32 v148, 16, v130
	v_and_b32_e32 v149, 0xffff0000, v130
	v_lshlrev_b32_e32 v150, 16, v131
	v_and_b32_e32 v151, 0xffff0000, v131
	v_lshlrev_b32_e32 v152, 16, v132
	v_and_b32_e32 v153, 0xffff0000, v132
	v_lshlrev_b32_e32 v154, 16, v133
	v_and_b32_e32 v155, 0xffff0000, v133
	v_lshlrev_b32_e32 v156, 16, v134
	v_and_b32_e32 v157, 0xffff0000, v134
	v_lshlrev_b32_e32 v158, 16, v135
	v_and_b32_e32 v159, 0xffff0000, v135
	v_pk_mul_f32 v[160:161], v[0:1], v[144:145]
	v_pk_mul_f32 v[162:163], v[8:9], v[152:153]
	v_pk_fma_f32 v[160:161], v[2:3], v[146:147], v[160:161]
	v_pk_fma_f32 v[162:163], v[10:11], v[154:155], v[162:163]
	v_pk_fma_f32 v[160:161], v[4:5], v[148:149], v[160:161]
	v_pk_fma_f32 v[162:163], v[12:13], v[156:157], v[162:163]
	v_pk_fma_f32 v[160:161], v[6:7], v[150:151], v[160:161]
	v_pk_fma_f32 v[162:163], v[14:15], v[158:159], v[162:163]
	v_pk_add_f32 v[160:161], v[160:161], v[162:163]
	s_nop 0
	v_add_f32_e32 v169, v160, v161
	v_pk_mul_f32 v[160:161], v[16:17], v[144:145]
	v_pk_mul_f32 v[162:163], v[24:25], v[152:153]
	v_pk_fma_f32 v[160:161], v[18:19], v[146:147], v[160:161]
	v_pk_fma_f32 v[162:163], v[26:27], v[154:155], v[162:163]
	v_pk_fma_f32 v[160:161], v[20:21], v[148:149], v[160:161]
	v_pk_fma_f32 v[162:163], v[28:29], v[156:157], v[162:163]
	v_pk_fma_f32 v[160:161], v[22:23], v[150:151], v[160:161]
	v_pk_fma_f32 v[162:163], v[30:31], v[158:159], v[162:163]
	v_pk_add_f32 v[160:161], v[160:161], v[162:163]
	s_nop 0
	v_add_f32_e32 v170, v160, v161
	v_pk_mul_f32 v[160:161], v[32:33], v[144:145]
	v_pk_mul_f32 v[162:163], v[40:41], v[152:153]
	v_pk_fma_f32 v[160:161], v[34:35], v[146:147], v[160:161]
	v_pk_fma_f32 v[162:163], v[42:43], v[154:155], v[162:163]
	v_pk_fma_f32 v[160:161], v[36:37], v[148:149], v[160:161]
	v_pk_fma_f32 v[162:163], v[44:45], v[156:157], v[162:163]
	v_pk_fma_f32 v[160:161], v[38:39], v[150:151], v[160:161]
	v_pk_fma_f32 v[162:163], v[46:47], v[158:159], v[162:163]
	v_pk_add_f32 v[160:161], v[160:161], v[162:163]
	s_nop 0
	v_add_f32_e32 v171, v160, v161
	v_pk_mul_f32 v[160:161], v[48:49], v[144:145]
	v_pk_mul_f32 v[162:163], v[56:57], v[152:153]
	v_pk_fma_f32 v[160:161], v[50:51], v[146:147], v[160:161]
	v_pk_fma_f32 v[162:163], v[58:59], v[154:155], v[162:163]
	v_pk_fma_f32 v[160:161], v[52:53], v[148:149], v[160:161]
	v_pk_fma_f32 v[162:163], v[60:61], v[156:157], v[162:163]
	v_pk_fma_f32 v[160:161], v[54:55], v[150:151], v[160:161]
	v_pk_fma_f32 v[162:163], v[62:63], v[158:159], v[162:163]
	v_pk_add_f32 v[160:161], v[160:161], v[162:163]
	s_nop 0
	v_add_f32_e32 v172, v160, v161
	v_pk_mul_f32 v[160:161], v[64:65], v[144:145]
	v_pk_mul_f32 v[162:163], v[72:73], v[152:153]
	v_pk_fma_f32 v[160:161], v[66:67], v[146:147], v[160:161]
	v_pk_fma_f32 v[162:163], v[74:75], v[154:155], v[162:163]
	v_pk_fma_f32 v[160:161], v[68:69], v[148:149], v[160:161]
	v_pk_fma_f32 v[162:163], v[76:77], v[156:157], v[162:163]
	v_pk_fma_f32 v[160:161], v[70:71], v[150:151], v[160:161]
	v_pk_fma_f32 v[162:163], v[78:79], v[158:159], v[162:163]
	v_pk_add_f32 v[160:161], v[160:161], v[162:163]
	s_nop 0
	v_add_f32_e32 v173, v160, v161
	s_nop 1
	v_permlane32_swap_b32_e32 v164, v169
	v_permlane32_swap_b32_e32 v165, v170
	v_permlane32_swap_b32_e32 v166, v171
	v_permlane32_swap_b32_e32 v167, v172
	v_permlane32_swap_b32_e32 v168, v173
	s_nop 1
	v_add_f32_e32 v96, v164, v169
	v_add_f32_e32 v97, v165, v170
	v_add_f32_e32 v98, v166, v171
	v_add_f32_e32 v99, v167, v172
	v_add_f32_e32 v100, v168, v173
	s_waitcnt vmcnt(0)
	v_lshlrev_b32_e32 v144, 16, v104
	v_and_b32_e32 v145, 0xffff0000, v104
	v_lshlrev_b32_e32 v146, 16, v105
	v_and_b32_e32 v147, 0xffff0000, v105
	v_lshlrev_b32_e32 v148, 16, v106
	v_and_b32_e32 v149, 0xffff0000, v106
	v_lshlrev_b32_e32 v150, 16, v107
	v_and_b32_e32 v151, 0xffff0000, v107
	v_lshlrev_b32_e32 v152, 16, v108
	v_and_b32_e32 v153, 0xffff0000, v108
	v_lshlrev_b32_e32 v154, 16, v109
	v_and_b32_e32 v155, 0xffff0000, v109
	v_lshlrev_b32_e32 v156, 16, v110
	v_and_b32_e32 v157, 0xffff0000, v110
	v_lshlrev_b32_e32 v158, 16, v111
	v_and_b32_e32 v159, 0xffff0000, v111
	v_pk_mul_f32 v[160:161], v[0:1], v[144:145]
	v_pk_mul_f32 v[162:163], v[8:9], v[152:153]
	v_pk_fma_f32 v[160:161], v[2:3], v[146:147], v[160:161]
	v_pk_fma_f32 v[162:163], v[10:11], v[154:155], v[162:163]
	v_pk_fma_f32 v[160:161], v[4:5], v[148:149], v[160:161]
	v_pk_fma_f32 v[162:163], v[12:13], v[156:157], v[162:163]
	v_pk_fma_f32 v[160:161], v[6:7], v[150:151], v[160:161]
	v_pk_fma_f32 v[162:163], v[14:15], v[158:159], v[162:163]
	v_pk_add_f32 v[160:161], v[160:161], v[162:163]
	s_nop 0
	v_add_f32_e32 v164, v160, v161
	v_pk_mul_f32 v[160:161], v[16:17], v[144:145]
	v_pk_mul_f32 v[162:163], v[24:25], v[152:153]
	v_pk_fma_f32 v[160:161], v[18:19], v[146:147], v[160:161]
	v_pk_fma_f32 v[162:163], v[26:27], v[154:155], v[162:163]
	v_pk_fma_f32 v[160:161], v[20:21], v[148:149], v[160:161]
	v_pk_fma_f32 v[162:163], v[28:29], v[156:157], v[162:163]
	v_pk_fma_f32 v[160:161], v[22:23], v[150:151], v[160:161]
	v_pk_fma_f32 v[162:163], v[30:31], v[158:159], v[162:163]
	v_pk_add_f32 v[160:161], v[160:161], v[162:163]
	s_nop 0
	v_add_f32_e32 v165, v160, v161
	v_pk_mul_f32 v[160:161], v[32:33], v[144:145]
	v_pk_mul_f32 v[162:163], v[40:41], v[152:153]
	v_pk_fma_f32 v[160:161], v[34:35], v[146:147], v[160:161]
	v_pk_fma_f32 v[162:163], v[42:43], v[154:155], v[162:163]
	v_pk_fma_f32 v[160:161], v[36:37], v[148:149], v[160:161]
	v_pk_fma_f32 v[162:163], v[44:45], v[156:157], v[162:163]
	v_pk_fma_f32 v[160:161], v[38:39], v[150:151], v[160:161]
	v_pk_fma_f32 v[162:163], v[46:47], v[158:159], v[162:163]
	v_pk_add_f32 v[160:161], v[160:161], v[162:163]
	s_nop 0
	v_add_f32_e32 v166, v160, v161
	v_pk_mul_f32 v[160:161], v[48:49], v[144:145]
	v_pk_mul_f32 v[162:163], v[56:57], v[152:153]
	v_pk_fma_f32 v[160:161], v[50:51], v[146:147], v[160:161]
	v_pk_fma_f32 v[162:163], v[58:59], v[154:155], v[162:163]
	v_pk_fma_f32 v[160:161], v[52:53], v[148:149], v[160:161]
	v_pk_fma_f32 v[162:163], v[60:61], v[156:157], v[162:163]
	v_pk_fma_f32 v[160:161], v[54:55], v[150:151], v[160:161]
	v_pk_fma_f32 v[162:163], v[62:63], v[158:159], v[162:163]
	v_pk_add_f32 v[160:161], v[160:161], v[162:163]
	s_nop 0
	v_add_f32_e32 v167, v160, v161
	v_pk_mul_f32 v[160:161], v[64:65], v[144:145]
	v_pk_mul_f32 v[162:163], v[72:73], v[152:153]
	v_pk_fma_f32 v[160:161], v[66:67], v[146:147], v[160:161]
	v_pk_fma_f32 v[162:163], v[74:75], v[154:155], v[162:163]
	v_pk_fma_f32 v[160:161], v[68:69], v[148:149], v[160:161]
	v_pk_fma_f32 v[162:163], v[76:77], v[156:157], v[162:163]
	v_pk_fma_f32 v[160:161], v[70:71], v[150:151], v[160:161]
	v_pk_fma_f32 v[162:163], v[78:79], v[158:159], v[162:163]
	v_pk_add_f32 v[160:161], v[160:161], v[162:163]
	s_nop 0
	v_add_f32_e32 v168, v160, v161
	v_lshlrev_b32_e32 v144, 16, v136
	v_and_b32_e32 v145, 0xffff0000, v136
	v_lshlrev_b32_e32 v146, 16, v137
	v_and_b32_e32 v147, 0xffff0000, v137
	v_lshlrev_b32_e32 v148, 16, v138
	v_and_b32_e32 v149, 0xffff0000, v138
	v_lshlrev_b32_e32 v150, 16, v139
	v_and_b32_e32 v151, 0xffff0000, v139
	v_lshlrev_b32_e32 v152, 16, v140
	v_and_b32_e32 v153, 0xffff0000, v140
	v_lshlrev_b32_e32 v154, 16, v141
	v_and_b32_e32 v155, 0xffff0000, v141
	v_lshlrev_b32_e32 v156, 16, v142
	v_and_b32_e32 v157, 0xffff0000, v142
	v_lshlrev_b32_e32 v158, 16, v143
	v_and_b32_e32 v159, 0xffff0000, v143
	v_pk_mul_f32 v[160:161], v[0:1], v[144:145]
	v_pk_mul_f32 v[162:163], v[8:9], v[152:153]
	v_pk_fma_f32 v[160:161], v[2:3], v[146:147], v[160:161]
	v_pk_fma_f32 v[162:163], v[10:11], v[154:155], v[162:163]
	v_pk_fma_f32 v[160:161], v[4:5], v[148:149], v[160:161]
	v_pk_fma_f32 v[162:163], v[12:13], v[156:157], v[162:163]
	v_pk_fma_f32 v[160:161], v[6:7], v[150:151], v[160:161]
	v_pk_fma_f32 v[162:163], v[14:15], v[158:159], v[162:163]
	v_pk_add_f32 v[160:161], v[160:161], v[162:163]
	s_nop 0
	v_add_f32_e32 v169, v160, v161
	v_pk_mul_f32 v[160:161], v[16:17], v[144:145]
	v_pk_mul_f32 v[162:163], v[24:25], v[152:153]
	v_pk_fma_f32 v[160:161], v[18:19], v[146:147], v[160:161]
	v_pk_fma_f32 v[162:163], v[26:27], v[154:155], v[162:163]
	v_pk_fma_f32 v[160:161], v[20:21], v[148:149], v[160:161]
	v_pk_fma_f32 v[162:163], v[28:29], v[156:157], v[162:163]
	v_pk_fma_f32 v[160:161], v[22:23], v[150:151], v[160:161]
	v_pk_fma_f32 v[162:163], v[30:31], v[158:159], v[162:163]
	v_pk_add_f32 v[160:161], v[160:161], v[162:163]
	s_nop 0
	v_add_f32_e32 v170, v160, v161
	v_pk_mul_f32 v[160:161], v[32:33], v[144:145]
	v_pk_mul_f32 v[162:163], v[40:41], v[152:153]
	v_pk_fma_f32 v[160:161], v[34:35], v[146:147], v[160:161]
	v_pk_fma_f32 v[162:163], v[42:43], v[154:155], v[162:163]
	v_pk_fma_f32 v[160:161], v[36:37], v[148:149], v[160:161]
	v_pk_fma_f32 v[162:163], v[44:45], v[156:157], v[162:163]
	v_pk_fma_f32 v[160:161], v[38:39], v[150:151], v[160:161]
	v_pk_fma_f32 v[162:163], v[46:47], v[158:159], v[162:163]
	v_pk_add_f32 v[160:161], v[160:161], v[162:163]
	s_nop 0
	v_add_f32_e32 v171, v160, v161
	v_pk_mul_f32 v[160:161], v[48:49], v[144:145]
	v_pk_mul_f32 v[162:163], v[56:57], v[152:153]
	v_pk_fma_f32 v[160:161], v[50:51], v[146:147], v[160:161]
	v_pk_fma_f32 v[162:163], v[58:59], v[154:155], v[162:163]
	v_pk_fma_f32 v[160:161], v[52:53], v[148:149], v[160:161]
	v_pk_fma_f32 v[162:163], v[60:61], v[156:157], v[162:163]
	v_pk_fma_f32 v[160:161], v[54:55], v[150:151], v[160:161]
	v_pk_fma_f32 v[162:163], v[62:63], v[158:159], v[162:163]
	v_pk_add_f32 v[160:161], v[160:161], v[162:163]
	s_nop 0
	v_add_f32_e32 v172, v160, v161
	v_pk_mul_f32 v[160:161], v[64:65], v[144:145]
	v_pk_mul_f32 v[162:163], v[72:73], v[152:153]
	v_pk_fma_f32 v[160:161], v[66:67], v[146:147], v[160:161]
	v_pk_fma_f32 v[162:163], v[74:75], v[154:155], v[162:163]
	v_pk_fma_f32 v[160:161], v[68:69], v[148:149], v[160:161]
	v_pk_fma_f32 v[162:163], v[76:77], v[156:157], v[162:163]
	v_pk_fma_f32 v[160:161], v[70:71], v[150:151], v[160:161]
	v_pk_fma_f32 v[162:163], v[78:79], v[158:159], v[162:163]
	v_pk_add_f32 v[160:161], v[160:161], v[162:163]
	s_nop 0
	v_add_f32_e32 v173, v160, v161
	s_nop 1
	v_permlane32_swap_b32_e32 v164, v169
	v_permlane32_swap_b32_e32 v165, v170
	v_permlane32_swap_b32_e32 v166, v171
	v_permlane32_swap_b32_e32 v167, v172
	v_permlane32_swap_b32_e32 v168, v173
	s_nop 1
	v_add_f32_e32 v104, v164, v169
	v_add_f32_e32 v105, v165, v170
	v_add_f32_e32 v106, v166, v171
	v_add_f32_e32 v107, v167, v172
	v_add_f32_e32 v108, v168, v173
	s_nop 1
	v_permlane16_swap_b32_e32 v80, v96
	v_permlane16_swap_b32_e32 v81, v97
	v_permlane16_swap_b32_e32 v82, v98
	v_permlane16_swap_b32_e32 v83, v99
	v_permlane16_swap_b32_e32 v84, v100
	v_permlane16_swap_b32_e32 v88, v104
	v_permlane16_swap_b32_e32 v89, v105
	v_permlane16_swap_b32_e32 v90, v106
	v_permlane16_swap_b32_e32 v91, v107
	v_permlane16_swap_b32_e32 v92, v108
	s_nop 1
	v_add_f32_e32 v80, v80, v96
	v_add_f32_e32 v81, v81, v97
	v_add_f32_e32 v82, v82, v98
	v_add_f32_e32 v83, v83, v99
	v_add_f32_e32 v84, v84, v100
	v_add_f32_e32 v88, v88, v104
	v_add_f32_e32 v89, v89, v105
	v_add_f32_e32 v90, v90, v106
	v_add_f32_e32 v91, v91, v107
	v_add_f32_e32 v92, v92, v108
	s_nop 1
	v_add_f32_dpp v80, v80, v80 quad_perm:[1,0,3,2] row_mask:0xf bank_mask:0xf
	v_add_f32_dpp v81, v81, v81 quad_perm:[1,0,3,2] row_mask:0xf bank_mask:0xf
	v_add_f32_dpp v82, v82, v82 quad_perm:[1,0,3,2] row_mask:0xf bank_mask:0xf
	v_add_f32_dpp v83, v83, v83 quad_perm:[1,0,3,2] row_mask:0xf bank_mask:0xf
	v_add_f32_dpp v84, v84, v84 quad_perm:[1,0,3,2] row_mask:0xf bank_mask:0xf
	v_add_f32_dpp v88, v88, v88 quad_perm:[1,0,3,2] row_mask:0xf bank_mask:0xf
	v_add_f32_dpp v89, v89, v89 quad_perm:[1,0,3,2] row_mask:0xf bank_mask:0xf
	v_add_f32_dpp v90, v90, v90 quad_perm:[1,0,3,2] row_mask:0xf bank_mask:0xf
	v_add_f32_dpp v91, v91, v91 quad_perm:[1,0,3,2] row_mask:0xf bank_mask:0xf
	v_add_f32_dpp v92, v92, v92 quad_perm:[1,0,3,2] row_mask:0xf bank_mask:0xf
	s_nop 1
	v_add_f32_dpp v80, v80, v80 quad_perm:[2,3,0,1] row_mask:0xf bank_mask:0xf
	v_add_f32_dpp v81, v81, v81 quad_perm:[2,3,0,1] row_mask:0xf bank_mask:0xf
	v_add_f32_dpp v82, v82, v82 quad_perm:[2,3,0,1] row_mask:0xf bank_mask:0xf
	v_add_f32_dpp v83, v83, v83 quad_perm:[2,3,0,1] row_mask:0xf bank_mask:0xf
	v_add_f32_dpp v84, v84, v84 quad_perm:[2,3,0,1] row_mask:0xf bank_mask:0xf
	v_add_f32_dpp v88, v88, v88 quad_perm:[2,3,0,1] row_mask:0xf bank_mask:0xf
	v_add_f32_dpp v89, v89, v89 quad_perm:[2,3,0,1] row_mask:0xf bank_mask:0xf
	v_add_f32_dpp v90, v90, v90 quad_perm:[2,3,0,1] row_mask:0xf bank_mask:0xf
	v_add_f32_dpp v91, v91, v91 quad_perm:[2,3,0,1] row_mask:0xf bank_mask:0xf
	v_add_f32_dpp v92, v92, v92 quad_perm:[2,3,0,1] row_mask:0xf bank_mask:0xf
	s_nop 1
	v_add_f32_dpp v80, v80, v80 row_ror:4 row_mask:0xf bank_mask:0xf
	v_add_f32_dpp v81, v81, v81 row_ror:4 row_mask:0xf bank_mask:0xf
	v_add_f32_dpp v82, v82, v82 row_ror:4 row_mask:0xf bank_mask:0xf
	v_add_f32_dpp v83, v83, v83 row_ror:4 row_mask:0xf bank_mask:0xf
	v_add_f32_dpp v84, v84, v84 row_ror:4 row_mask:0xf bank_mask:0xf
	v_add_f32_dpp v88, v88, v88 row_ror:4 row_mask:0xf bank_mask:0xf
	v_add_f32_dpp v89, v89, v89 row_ror:4 row_mask:0xf bank_mask:0xf
	v_add_f32_dpp v90, v90, v90 row_ror:4 row_mask:0xf bank_mask:0xf
	v_add_f32_dpp v91, v91, v91 row_ror:4 row_mask:0xf bank_mask:0xf
	v_add_f32_dpp v92, v92, v92 row_ror:4 row_mask:0xf bank_mask:0xf
	s_nop 1
	v_add_f32_dpp v80, v80, v80 row_ror:8 row_mask:0xf bank_mask:0xf
	v_add_f32_dpp v81, v81, v81 row_ror:8 row_mask:0xf bank_mask:0xf
	v_add_f32_dpp v82, v82, v82 row_ror:8 row_mask:0xf bank_mask:0xf
	v_add_f32_dpp v83, v83, v83 row_ror:8 row_mask:0xf bank_mask:0xf
	v_add_f32_dpp v84, v84, v84 row_ror:8 row_mask:0xf bank_mask:0xf
	v_add_f32_dpp v88, v88, v88 row_ror:8 row_mask:0xf bank_mask:0xf
	v_add_f32_dpp v89, v89, v89 row_ror:8 row_mask:0xf bank_mask:0xf
	v_add_f32_dpp v90, v90, v90 row_ror:8 row_mask:0xf bank_mask:0xf
	v_add_f32_dpp v91, v91, v91 row_ror:8 row_mask:0xf bank_mask:0xf
	v_add_f32_dpp v92, v92, v92 row_ror:8 row_mask:0xf bank_mask:0xf
	s_nop 1
	v_and_b32_e32 v160, 63, v229
	v_lshrrev_b32_e32 v161, 6, v229
	v_lshrrev_b32_e32 v162, 4, v160
	v_lshlrev_b32_e32 v162, 1, v162
	v_lshl_add_u32 v162, v161, 3, v162
	s_lshl_b32 s52, s2, 5
	v_add_u32_e32 v162, s52, v162
	s_cmp_eq_u32 s48, 0
	s_cbranch_scc1 .Lbias_col0
	v_lshrrev_b32_e32 v163, 8, v162
	v_lshlrev_b32_e32 v163, 7, v163
	v_and_b32_e32 v164, 0x7f, v162
	v_add_u32_e32 v163, v163, v164
	v_bfe_u32 v164, v162, 7, 1
	v_mul_u32_u24_e32 v164, 0xb00, v164
	v_add_u32_e32 v162, v163, v164
.Lbias_col0:
	v_lshlrev_b32_e32 v162, 2, v162
	v_add_u32_e32 v163, s46, v162
	v_add_u32_e32 v164, s46, v163
	v_add_u32_e32 v165, s46, v164
	v_add_u32_e32 v166, s46, v165
	v_and_b32_e32 v160, 15, v160
	v_cmp_eq_u32_e64 s[52:53], 0, v160
	s_nop 4
	s_and_b64 exec, exec, s[52:53]
	global_store_dword v162, v80, s[44:45]
	global_store_dword v162, v88, s[44:45] offset:4
	global_store_dword v163, v81, s[44:45]
	global_store_dword v163, v89, s[44:45] offset:4
	global_store_dword v164, v82, s[44:45]
	global_store_dword v164, v90, s[44:45] offset:4
	global_store_dword v165, v83, s[44:45]
	global_store_dword v165, v91, s[44:45] offset:4
	global_store_dword v166, v84, s[44:45]
	global_store_dword v166, v92, s[44:45] offset:4
	s_mov_b64 exec, s[50:51]
	v_mul_u32_u24_e32 v0, 0xc0, v228
	ds_read_b128 v[128:131], v0 offset:0
	ds_read_b128 v[132:135], v0 offset:16
	ds_read_b128 v[136:139], v0 offset:32
	ds_read_b128 v[140:143], v0 offset:48
	ds_read_b128 v[144:147], v0 offset:64
	ds_read_b128 v[148:151], v0 offset:80
	ds_read_b128 v[152:155], v0 offset:96
	ds_read_b128 v[156:159], v0 offset:112
	ds_read_b128 v[160:163], v0 offset:128
	ds_read_b128 v[164:167], v0 offset:144
	ds_read_b128 v[168:171], v0 offset:160
	ds_read_b128 v[172:175], v0 offset:176
	s_mov_b32 s28, s49
	v_readlane_b32 s40, v255, 42
	v_readlane_b32 s41, v255, 43
	v_readlane_b32 s42, v255, 44
	v_readlane_b32 s43, v255, 45
	v_readlane_b32 s44, v255, 46
	v_readlane_b32 s45, v255, 47
	v_readlane_b32 s46, v255, 48
	v_readlane_b32 s47, v255, 49
	v_readlane_b32 s48, v255, 50
	v_readlane_b32 s49, v255, 51
	v_readlane_b32 s50, v255, 52
	v_readlane_b32 s51, v255, 53
	v_readlane_b32 s52, v255, 54
	v_readlane_b32 s53, v255, 55
	s_waitcnt lgkmcnt(0)
	s_nop 3
	s_cmp_eq_u32 s28, 1
	s_cbranch_scc1 .Lbias_ret1
	s_cmp_eq_u32 s28, 2
	s_cbranch_scc1 .Lbias_ret2
	s_branch .Lbias_ret3
.Lbias_ret1:
.Lbias_ret3:
	s_endpgm
